# in-proj scheduler: 8x4 XCD patches (token rows, cols 0-31) with the patch column rotated per round across XCDs; 16x2 for cols 32-33 and context rows
# speedup vs baseline: 1.0070x; 1.0070x over previous
.LBB0_590:
	s_andn2_b64 vcc, exec, s[54:55]
	s_cbranch_vccnz .LBB0_594
	s_and_b32 s44, s37, 7
	s_add_i32 s39, s30, s44
	s_cmpk_gt_u32 s39, 0x98
	s_mov_b64 s[20:21], 0
	s_cbranch_scc1 .LBB0_593
	s_lshr_b32 s20, s37, 3
	s_cmpk_lt_u32 s39, 0x80
	s_cbranch_scc0 .Lsp_r2_ipf0
	s_and_b32 s34, s39, -8
	s_lshr_b32 s21, s20, 2
	s_add_i32 s34, s34, s21
	s_lshr_b32 s35, s39, 3
	s_add_i32 s35, s35, s39
	s_and_b32 s35, s35, 7
	s_lshl_b32 s35, s35, 2
	s_and_b32 s21, s20, 3
	s_add_i32 s35, s35, s21
	s_branch .Lsp_dn_ipf0

.LBB0_627:
	s_andn2_b64 vcc, exec, s[66:67]
	s_cbranch_vccnz .LBB0_631
	s_and_b32 s62, s68, 7
	s_add_i32 s39, s30, s62
	s_cmpk_gt_u32 s39, 0x98
	s_mov_b64 s[20:21], 0
	s_cbranch_scc1 .LBB0_630
	s_lshr_b32 s20, s68, 3
	s_cmpk_lt_u32 s39, 0x80
	s_cbranch_scc0 .Lsp_r2_ipl0
	s_and_b32 s37, s39, -8
	s_lshr_b32 s21, s20, 2
	s_add_i32 s37, s37, s21
	s_lshr_b32 s65, s39, 3
	s_add_i32 s65, s65, s39
	s_and_b32 s65, s65, 7
	s_lshl_b32 s65, s65, 2
	s_and_b32 s21, s20, 3
	s_add_i32 s65, s65, s21
	s_branch .Lsp_dn_ipl0
